# the two expert weight conversions that run beside the top-k selection use the same software-pipelined loop with non-temporal loads and stores
# speedup vs baseline: 1.0324x; 1.0014x over previous
; #define LAS __attribute__((address_space(3)))
; __device__ __forceinline__ unsigned cvt_pk_bf16(float lo, float hi) { unsigned r; asm("v_cvt_pk_bf16_f32 %0, %1, %2" : "=v"(r) : "v"(lo), "v"(hi)); return r; }
;     ...
;     for (int gi = bid; gi * 4 < total; gi += nb) {
;         f32x4 v[4][2];
; #pragma unroll
;         for (int q = 0; q < 4; ++q) { const int it = gi * 4 + q;
;             v[q][0] = (f32x4){0.f, 0.f, 0.f, 0.f}; v[q][1] = (f32x4){0.f, 0.f, 0.f, 0.f};
;             if (it < total) { const int b = it / per, r = it % per, k0 = (r / tn) * 64, n0 = (r % tn) * 64;
;                 const float* sp = src + (size_t)b * sbs + (size_t)k0 * N + n0; const int c4 = (tid & 15) * 4;
;                 if (n0 + c4 < N) { v[q][0] = *(const f32x4*)(sp + (size_t)(tid >> 4) * N + c4); v[q][1] = *(const f32x4*)(sp + (size_t)((tid >> 4) + 32) * N + c4); } } }
; #pragma unroll
;         for (int q = 0; q < 4; ++q)
; #pragma unroll
;             for (int j = 0; j < 2; ++j) { const int row = (tid >> 4) + 32 * j, c4 = (tid & 15) * 4; LAS float* tp = tile + q * (64 * 65) + row * 65 + c4;
;                 tp[0] = v[q][j][0]; tp[1] = v[q][j][1]; tp[2] = v[q][j][2]; tp[3] = v[q][j][3]; }
;         __syncthreads();
; #pragma unroll
;         for (int q = 0; q < 4; ++q) { const int it = gi * 4 + q;
;             if (it < total) { const int b = it / per, r = it % per, k0 = (r / tn) * 64, n0 = (r % tn) * 64;
;                 const int n = tid >> 3, kc = (tid & 7) * 8;
;                 if (n0 + n < N) { float f[8];
; #pragma unroll
;                     for (int j = 0; j < 8; ++j) f[j] = tile[q * (64 * 65) + (kc + j) * 65 + n];
;                     u32x4 w; w.x = cvt_pk_bf16(f[0], f[1]); w.y = cvt_pk_bf16(f[2], f[3]); w.z = cvt_pk_bf16(f[4], f[5]); w.w = cvt_pk_bf16(f[6], f[7]);
;                     int nd = n0 + n + nshift; if (nd >= N) nd -= N;
;                     *(u32x4*)(dst + (size_t)b * dbs + (size_t)nd * ldd + kofs + k0 + kc) = w; } } }
;         __syncthreads();
; __device__ void phase_topk(const Params& p, int l, LAS unsigned char* lds) {
;     ...
;         if (l == 1 && gridDim.x > NE) cvt_job((LAS float*)lds, p.ewg + (size_t)NE * FF * 1024, (bf16_t*)(p.ws + WS_WG) + (size_t)NE * FF * 1024, NE, 1024, FF, 1024, 0, (size_t)1024 * FF, (size_t)FF * 1024, (int)blockIdx.x - NE, (int)gridDim.x - NE);
.LBB0_239:
	s_and_b64 vcc, exec, s[4:5]
	s_cbranch_vccz .LBB0_309
	s_cmp_lt_i32 s26, 1
	s_mov_b64 s[4:5], -1
	s_cbranch_scc1 .LBB0_275
	s_cmp_eq_u32 s26, 1
	s_cbranch_scc0 .LBB0_274
	v_readlane_b32 s4, v252, 30
	v_readlane_b32 s5, v252, 31
	s_andn2_b64 vcc, exec, s[4:5]
	s_cbranch_vccnz .LBB0_274
	v_readlane_b32 s4, v252, 37
	v_readlane_b32 s5, v252, 38
	s_waitcnt vmcnt(0)
	v_mov_b32_e32 v0, v213
	s_andn2_b64 vcc, exec, s[4:5]
	s_cbranch_vccnz .LBB0_274
	v_lshrrev_b32_e32 v96, 4, v213
	v_and_b32_e32 v97, 15, v213
	v_lshlrev_b32_e32 v97, 4, v97
	v_mul_u32_u24_e32 v98, 0x2000, v96
	v_add_u32_e32 v98, v98, v97
	v_add_u32_e32 v99, 0x40000, v98
	v_lshrrev_b32_e32 v100, 3, v213
	v_and_b32_e32 v101, 7, v213
	v_lshlrev_b32_e32 v102, 4, v101
	v_mul_u32_u24_e32 v103, 0x800, v100
	v_add_u32_e32 v103, v103, v102
	v_mul_u32_u24_e32 v104, 0x104, v96
	v_add_u32_e32 v104, v104, v97
	v_mul_u32_u24_e32 v105, 0x820, v101
	v_lshl_add_u32 v105, v100, 2, v105
	v_mov_b32_e32 v80, v104
	v_mov_b32_e32 v88, v105
	v_add_u32_e32 v81, 0x2080, v104
	v_add_u32_e32 v89, 0x400, v105
	v_add_u32_e32 v82, 0x4100, v104
	v_add_u32_e32 v90, 0x4100, v105
	v_add_u32_e32 v83, 0x6180, v104
	v_add_u32_e32 v91, 0x4500, v105
	v_add_u32_e32 v84, 0x8200, v104
	v_add_u32_e32 v92, 0x8200, v105
	v_add_u32_e32 v85, 0xa280, v104
	v_add_u32_e32 v93, 0x8600, v105
	v_add_u32_e32 v86, 0xc300, v104
	v_add_u32_e32 v94, 0xc300, v105
	v_add_u32_e32 v87, 0xe380, v104
	v_add_u32_e32 v95, 0xc700, v105
	s_mov_b32 s12, s85
	v_readlane_b32 s13, v252, 56
	v_readlane_b32 s14, v252, 57
	v_readlane_b32 s15, v252, 58
	v_readlane_b32 s20, v252, 39
	v_readlane_b32 s19, v252, 36
	s_lshr_b32 s16, s20, 7
	s_lshl_b32 s16, s16, 23
	s_bfe_u32 s17, s20, 0x40003
	s_lshl_b32 s17, s17, 19
	s_add_u32 s16, s16, s17
	s_and_b32 s17, s20, 7
	s_lshl_b32 s17, s17, 10
	s_add_u32 s16, s16, s17
	s_add_u32 s6, s12, s16
	s_addc_u32 s7, s13, 0
	global_load_dwordx4 v[0:3], v98, s[6:7] nt
	global_load_dwordx4 v[4:7], v99, s[6:7] nt
	global_load_dwordx4 v[8:11], v98, s[6:7] offset:256 nt
	global_load_dwordx4 v[12:15], v99, s[6:7] offset:256 nt
	global_load_dwordx4 v[16:19], v98, s[6:7] offset:512 nt
	global_load_dwordx4 v[20:23], v99, s[6:7] offset:512 nt
	global_load_dwordx4 v[24:27], v98, s[6:7] offset:768 nt
	global_load_dwordx4 v[28:31], v99, s[6:7] offset:768 nt
.Lcv_tkewg_loop:
	s_lshr_b32 s16, s20, 7
	s_lshl_b32 s16, s16, 22
	s_and_b32 s17, s20, 7
	s_lshl_b32 s17, s17, 19
	s_add_u32 s16, s16, s17
	s_bfe_u32 s17, s20, 0x40003
	s_lshl_b32 s17, s17, 7
	s_add_u32 s16, s16, s17
	s_add_u32 s8, s14, s16
	s_addc_u32 s9, s15, 0
	s_waitcnt vmcnt(0)
	ds_write2_b32 v80, v0, v1 offset1:1
	ds_write2_b32 v80, v2, v3 offset0:2 offset1:3
	ds_write2_b32 v81, v4, v5 offset1:1
	ds_write2_b32 v81, v6, v7 offset0:2 offset1:3
	ds_write2_b32 v82, v8, v9 offset1:1
	ds_write2_b32 v82, v10, v11 offset0:2 offset1:3
	ds_write2_b32 v83, v12, v13 offset1:1
	ds_write2_b32 v83, v14, v15 offset0:2 offset1:3
	ds_write2_b32 v84, v16, v17 offset1:1
	ds_write2_b32 v84, v18, v19 offset0:2 offset1:3
	ds_write2_b32 v85, v20, v21 offset1:1
	ds_write2_b32 v85, v22, v23 offset0:2 offset1:3
	ds_write2_b32 v86, v24, v25 offset1:1
	ds_write2_b32 v86, v26, v27 offset0:2 offset1:3
	ds_write2_b32 v87, v28, v29 offset1:1
	ds_write2_b32 v87, v30, v31 offset0:2 offset1:3
	s_add_i32 s21, s20, s19
	s_cmpk_lt_i32 s21, 0x800
	s_cbranch_scc0 .Lcv_tkewg_nopf
	s_lshr_b32 s16, s21, 7
	s_lshl_b32 s16, s16, 23
	s_bfe_u32 s17, s21, 0x40003
	s_lshl_b32 s17, s17, 19
	s_add_u32 s16, s16, s17
	s_and_b32 s17, s21, 7
	s_lshl_b32 s17, s17, 10
	s_add_u32 s16, s16, s17
	s_add_u32 s6, s12, s16
	s_addc_u32 s7, s13, 0
	global_load_dwordx4 v[0:3], v98, s[6:7] nt
	global_load_dwordx4 v[4:7], v99, s[6:7] nt
	global_load_dwordx4 v[8:11], v98, s[6:7] offset:256 nt
	global_load_dwordx4 v[12:15], v99, s[6:7] offset:256 nt
	global_load_dwordx4 v[16:19], v98, s[6:7] offset:512 nt
	global_load_dwordx4 v[20:23], v99, s[6:7] offset:512 nt
	global_load_dwordx4 v[24:27], v98, s[6:7] offset:768 nt
	global_load_dwordx4 v[28:31], v99, s[6:7] offset:768 nt
.Lcv_tkewg_nopf:
	s_waitcnt lgkmcnt(0)
	s_barrier
	ds_read2_b32 v[32:33], v88 offset1:65
	ds_read2_b32 v[34:35], v88 offset0:130 offset1:195
	ds_read2_b32 v[36:37], v89 offset0:4 offset1:69
	ds_read2_b32 v[38:39], v89 offset0:134 offset1:199
	ds_read2_b32 v[40:41], v90 offset1:65
	ds_read2_b32 v[42:43], v90 offset0:130 offset1:195
	ds_read2_b32 v[44:45], v91 offset0:4 offset1:69
	ds_read2_b32 v[46:47], v91 offset0:134 offset1:199
	ds_read2_b32 v[48:49], v92 offset1:65
	ds_read2_b32 v[50:51], v92 offset0:130 offset1:195
	ds_read2_b32 v[52:53], v93 offset0:4 offset1:69
	ds_read2_b32 v[54:55], v93 offset0:134 offset1:199
	ds_read2_b32 v[56:57], v94 offset1:65
	ds_read2_b32 v[58:59], v94 offset0:130 offset1:195
	ds_read2_b32 v[60:61], v95 offset0:4 offset1:69
	ds_read2_b32 v[62:63], v95 offset0:134 offset1:199
	s_waitcnt lgkmcnt(12)
	v_cvt_pk_bf16_f32 v64, v32, v33
	v_cvt_pk_bf16_f32 v65, v34, v35
	v_cvt_pk_bf16_f32 v66, v36, v37
	v_cvt_pk_bf16_f32 v67, v38, v39
	global_store_dwordx4 v103, v[64:67], s[8:9] nt
	s_waitcnt lgkmcnt(8)
	v_cvt_pk_bf16_f32 v68, v40, v41
	v_cvt_pk_bf16_f32 v69, v42, v43
	v_cvt_pk_bf16_f32 v70, v44, v45
	v_cvt_pk_bf16_f32 v71, v46, v47
	s_add_u32 s10, s8, 0x20000
	s_addc_u32 s11, s9, 0
	global_store_dwordx4 v103, v[68:71], s[10:11] nt
	s_waitcnt lgkmcnt(4)
	v_cvt_pk_bf16_f32 v72, v48, v49
	v_cvt_pk_bf16_f32 v73, v50, v51
	v_cvt_pk_bf16_f32 v74, v52, v53
	v_cvt_pk_bf16_f32 v75, v54, v55
	s_add_u32 s10, s8, 0x40000
	s_addc_u32 s11, s9, 0
	global_store_dwordx4 v103, v[72:75], s[10:11] nt
	s_waitcnt lgkmcnt(0)
	v_cvt_pk_bf16_f32 v76, v56, v57
	v_cvt_pk_bf16_f32 v77, v58, v59
	v_cvt_pk_bf16_f32 v78, v60, v61
	v_cvt_pk_bf16_f32 v79, v62, v63
	s_add_u32 s10, s8, 0x60000
	s_addc_u32 s11, s9, 0
	global_store_dwordx4 v103, v[76:79], s[10:11] nt
	s_barrier
	s_mov_b32 s20, s21
	s_cmpk_lt_i32 s20, 0x800
	s_cbranch_scc1 .Lcv_tkewg_loop
; #define LAS __attribute__((address_space(3)))
; __device__ __forceinline__ unsigned cvt_pk_bf16(float lo, float hi) { unsigned r; asm("v_cvt_pk_bf16_f32 %0, %1, %2" : "=v"(r) : "v"(lo), "v"(hi)); return r; }
;     ...
;     for (int gi = bid; gi * 4 < total; gi += nb) {
;         f32x4 v[4][2];
; #pragma unroll
;         for (int q = 0; q < 4; ++q) { const int it = gi * 4 + q;
;             v[q][0] = (f32x4){0.f, 0.f, 0.f, 0.f}; v[q][1] = (f32x4){0.f, 0.f, 0.f, 0.f};
;             if (it < total) { const int b = it / per, r = it % per, k0 = (r / tn) * 64, n0 = (r % tn) * 64;
;                 const float* sp = src + (size_t)b * sbs + (size_t)k0 * N + n0; const int c4 = (tid & 15) * 4;
;                 if (n0 + c4 < N) { v[q][0] = *(const f32x4*)(sp + (size_t)(tid >> 4) * N + c4); v[q][1] = *(const f32x4*)(sp + (size_t)((tid >> 4) + 32) * N + c4); } } }
; #pragma unroll
;         for (int q = 0; q < 4; ++q)
; #pragma unroll
;             for (int j = 0; j < 2; ++j) { const int row = (tid >> 4) + 32 * j, c4 = (tid & 15) * 4; LAS float* tp = tile + q * (64 * 65) + row * 65 + c4;
;                 tp[0] = v[q][j][0]; tp[1] = v[q][j][1]; tp[2] = v[q][j][2]; tp[3] = v[q][j][3]; }
;         __syncthreads();
; #pragma unroll
;         for (int q = 0; q < 4; ++q) { const int it = gi * 4 + q;
;             if (it < total) { const int b = it / per, r = it % per, k0 = (r / tn) * 64, n0 = (r % tn) * 64;
;                 const int n = tid >> 3, kc = (tid & 7) * 8;
;                 if (n0 + n < N) { float f[8];
; #pragma unroll
;                     for (int j = 0; j < 8; ++j) f[j] = tile[q * (64 * 65) + (kc + j) * 65 + n];
;                     u32x4 w; w.x = cvt_pk_bf16(f[0], f[1]); w.y = cvt_pk_bf16(f[2], f[3]); w.z = cvt_pk_bf16(f[4], f[5]); w.w = cvt_pk_bf16(f[6], f[7]);
;                     int nd = n0 + n + nshift; if (nd >= N) nd -= N;
;                     *(u32x4*)(dst + (size_t)b * dbs + (size_t)nd * ldd + kofs + k0 + kc) = w; } } }
;         __syncthreads();
; __device__ void phase_topk(const Params& p, int l, LAS unsigned char* lds) {
;     ...
;         if (l == 0 && gridDim.x > NE) cvt_job((LAS float*)lds, p.ewd + (size_t)NE * FF * 1024, (bf16_t*)(p.ws + WS_WD) + (size_t)NE * FF * 1024, NE, FF, 1024, FF, 0, (size_t)FF * 1024, (size_t)1024 * FF, (int)blockIdx.x - NE, (int)gridDim.x - NE);
.LBB0_274:
	s_mov_b64 s[4:5], 0
.LBB0_275:
	s_andn2_b64 vcc, exec, s[4:5]
	s_cbranch_vccnz .LBB0_309
	s_cmp_eq_u32 s26, 0
	s_cbranch_scc0 .LBB0_309
	v_readlane_b32 s4, v252, 30
	v_readlane_b32 s5, v252, 31
	s_andn2_b64 vcc, exec, s[4:5]
	s_cbranch_vccnz .LBB0_309
	v_readlane_b32 s4, v252, 37
	v_readlane_b32 s5, v252, 38
	s_waitcnt vmcnt(0)
	v_mov_b32_e32 v0, v213
	s_andn2_b64 vcc, exec, s[4:5]
	s_cbranch_vccnz .LBB0_309
	v_lshrrev_b32_e32 v96, 4, v213
	v_and_b32_e32 v97, 15, v213
	v_lshlrev_b32_e32 v97, 4, v97
	v_mul_u32_u24_e32 v98, 0x1000, v96
	v_add_u32_e32 v98, v98, v97
	v_add_u32_e32 v99, 0x20000, v98
	v_lshrrev_b32_e32 v100, 3, v213
	v_and_b32_e32 v101, 7, v213
	v_lshlrev_b32_e32 v102, 4, v101
	v_mul_u32_u24_e32 v103, 0x1000, v100
	v_add_u32_e32 v103, v103, v102
	v_mul_u32_u24_e32 v104, 0x104, v96
	v_add_u32_e32 v104, v104, v97
	v_mul_u32_u24_e32 v105, 0x820, v101
	v_lshl_add_u32 v105, v100, 2, v105
	v_mov_b32_e32 v80, v104
	v_mov_b32_e32 v88, v105
	v_add_u32_e32 v81, 0x2080, v104
	v_add_u32_e32 v89, 0x400, v105
	v_add_u32_e32 v82, 0x4100, v104
	v_add_u32_e32 v90, 0x4100, v105
	v_add_u32_e32 v83, 0x6180, v104
	v_add_u32_e32 v91, 0x4500, v105
	v_add_u32_e32 v84, 0x8200, v104
	v_add_u32_e32 v92, 0x8200, v105
	v_add_u32_e32 v85, 0xa280, v104
	v_add_u32_e32 v93, 0x8600, v105
	v_add_u32_e32 v86, 0xc300, v104
	v_add_u32_e32 v94, 0xc300, v105
	v_add_u32_e32 v87, 0xe380, v104
	v_add_u32_e32 v95, 0xc700, v105
	v_readlane_b32 s12, v252, 32
	v_readlane_b32 s13, v252, 33
	v_readlane_b32 s14, v252, 34
	v_readlane_b32 s15, v252, 35
	v_readlane_b32 s20, v252, 39
	v_readlane_b32 s19, v252, 36
	s_lshr_b32 s16, s20, 7
	s_lshl_b32 s16, s16, 23
	s_bfe_u32 s17, s20, 0x50002
	s_lshl_b32 s17, s17, 18
	s_add_u32 s16, s16, s17
	s_and_b32 s17, s20, 3
	s_lshl_b32 s17, s17, 10
	s_add_u32 s16, s16, s17
	s_add_u32 s6, s12, s16
	s_addc_u32 s7, s13, 0
	global_load_dwordx4 v[0:3], v98, s[6:7] nt
	global_load_dwordx4 v[4:7], v99, s[6:7] nt
	global_load_dwordx4 v[8:11], v98, s[6:7] offset:256 nt
	global_load_dwordx4 v[12:15], v99, s[6:7] offset:256 nt
	global_load_dwordx4 v[16:19], v98, s[6:7] offset:512 nt
	global_load_dwordx4 v[20:23], v99, s[6:7] offset:512 nt
	global_load_dwordx4 v[24:27], v98, s[6:7] offset:768 nt
	global_load_dwordx4 v[28:31], v99, s[6:7] offset:768 nt
.Lcv_tkewd_loop:
	s_lshr_b32 s16, s20, 7
	s_lshl_b32 s16, s16, 22
	s_and_b32 s17, s20, 3
	s_lshl_b32 s17, s17, 20
	s_add_u32 s16, s16, s17
	s_bfe_u32 s17, s20, 0x50002
	s_lshl_b32 s17, s17, 7
	s_add_u32 s16, s16, s17
	s_add_u32 s8, s14, s16
	s_addc_u32 s9, s15, 0
	s_waitcnt vmcnt(0)
	ds_write2_b32 v80, v0, v1 offset1:1
	ds_write2_b32 v80, v2, v3 offset0:2 offset1:3
	ds_write2_b32 v81, v4, v5 offset1:1
	ds_write2_b32 v81, v6, v7 offset0:2 offset1:3
	ds_write2_b32 v82, v8, v9 offset1:1
	ds_write2_b32 v82, v10, v11 offset0:2 offset1:3
	ds_write2_b32 v83, v12, v13 offset1:1
	ds_write2_b32 v83, v14, v15 offset0:2 offset1:3
	ds_write2_b32 v84, v16, v17 offset1:1
	ds_write2_b32 v84, v18, v19 offset0:2 offset1:3
	ds_write2_b32 v85, v20, v21 offset1:1
	ds_write2_b32 v85, v22, v23 offset0:2 offset1:3
	ds_write2_b32 v86, v24, v25 offset1:1
	ds_write2_b32 v86, v26, v27 offset0:2 offset1:3
	ds_write2_b32 v87, v28, v29 offset1:1
	ds_write2_b32 v87, v30, v31 offset0:2 offset1:3
	s_add_i32 s21, s20, s19
	s_cmpk_lt_i32 s21, 0x800
	s_cbranch_scc0 .Lcv_tkewd_nopf
	s_lshr_b32 s16, s21, 7
	s_lshl_b32 s16, s16, 23
	s_bfe_u32 s17, s21, 0x50002
	s_lshl_b32 s17, s17, 18
	s_add_u32 s16, s16, s17
	s_and_b32 s17, s21, 3
	s_lshl_b32 s17, s17, 10
	s_add_u32 s16, s16, s17
	s_add_u32 s6, s12, s16
	s_addc_u32 s7, s13, 0
	global_load_dwordx4 v[0:3], v98, s[6:7] nt
	global_load_dwordx4 v[4:7], v99, s[6:7] nt
	global_load_dwordx4 v[8:11], v98, s[6:7] offset:256 nt
	global_load_dwordx4 v[12:15], v99, s[6:7] offset:256 nt
	global_load_dwordx4 v[16:19], v98, s[6:7] offset:512 nt
	global_load_dwordx4 v[20:23], v99, s[6:7] offset:512 nt
	global_load_dwordx4 v[24:27], v98, s[6:7] offset:768 nt
	global_load_dwordx4 v[28:31], v99, s[6:7] offset:768 nt
.Lcv_tkewd_nopf:
	s_waitcnt lgkmcnt(0)
	s_barrier
	ds_read2_b32 v[32:33], v88 offset1:65
	ds_read2_b32 v[34:35], v88 offset0:130 offset1:195
	ds_read2_b32 v[36:37], v89 offset0:4 offset1:69
	ds_read2_b32 v[38:39], v89 offset0:134 offset1:199
	ds_read2_b32 v[40:41], v90 offset1:65
	ds_read2_b32 v[42:43], v90 offset0:130 offset1:195
	ds_read2_b32 v[44:45], v91 offset0:4 offset1:69
	ds_read2_b32 v[46:47], v91 offset0:134 offset1:199
	ds_read2_b32 v[48:49], v92 offset1:65
	ds_read2_b32 v[50:51], v92 offset0:130 offset1:195
	ds_read2_b32 v[52:53], v93 offset0:4 offset1:69
	ds_read2_b32 v[54:55], v93 offset0:134 offset1:199
	ds_read2_b32 v[56:57], v94 offset1:65
	ds_read2_b32 v[58:59], v94 offset0:130 offset1:195
	ds_read2_b32 v[60:61], v95 offset0:4 offset1:69
	ds_read2_b32 v[62:63], v95 offset0:134 offset1:199
	s_waitcnt lgkmcnt(12)
	v_cvt_pk_bf16_f32 v64, v32, v33
	v_cvt_pk_bf16_f32 v65, v34, v35
	v_cvt_pk_bf16_f32 v66, v36, v37
	v_cvt_pk_bf16_f32 v67, v38, v39
	global_store_dwordx4 v103, v[64:67], s[8:9] nt
	s_waitcnt lgkmcnt(8)
	v_cvt_pk_bf16_f32 v68, v40, v41
	v_cvt_pk_bf16_f32 v69, v42, v43
	v_cvt_pk_bf16_f32 v70, v44, v45
	v_cvt_pk_bf16_f32 v71, v46, v47
	s_add_u32 s10, s8, 0x40000
	s_addc_u32 s11, s9, 0
	global_store_dwordx4 v103, v[68:71], s[10:11] nt
	s_waitcnt lgkmcnt(4)
	v_cvt_pk_bf16_f32 v72, v48, v49
	v_cvt_pk_bf16_f32 v73, v50, v51
	v_cvt_pk_bf16_f32 v74, v52, v53
	v_cvt_pk_bf16_f32 v75, v54, v55
	s_add_u32 s10, s8, 0x80000
	s_addc_u32 s11, s9, 0
	global_store_dwordx4 v103, v[72:75], s[10:11] nt
	s_waitcnt lgkmcnt(0)
	v_cvt_pk_bf16_f32 v76, v56, v57
	v_cvt_pk_bf16_f32 v77, v58, v59
	v_cvt_pk_bf16_f32 v78, v60, v61
	v_cvt_pk_bf16_f32 v79, v62, v63
	s_add_u32 s10, s8, 0xc0000
	s_addc_u32 s11, s9, 0
	global_store_dwordx4 v103, v[76:79], s[10:11] nt
	s_barrier
	s_mov_b32 s20, s21
	s_cmpk_lt_i32 s20, 0x800
	s_cbranch_scc1 .Lcv_tkewd_loop
.LBB0_309:
	s_mov_b64 s[4:5], 0
